# HGRN scan: two-steps-ahead operand prefetch with loads spread behind the MFMAs (second register set, loop unrolled by two); HGRN waves take 10 of 11 conversion rounds
# speedup vs baseline: 1.0073x; 1.0073x over previous
.LBB0_499:
	s_lshl_b32 s14, s4, 1
	s_or_b32 s14, s14, s11
	s_ashr_i32 s15, s14, 31
	s_lshl_b64 s[14:15], s[14:15], 18
	s_add_u32 s11, s72, s14
	s_addc_u32 s14, s73, s15
	s_lshl_b32 s13, s13, 2
	s_add_u32 s11, s11, s13
	s_addc_u32 s13, s14, 0
	s_lshl_b32 s14, s8, 6
	s_add_u32 s14, s11, s14
	s_addc_u32 s15, s13, 0
	v_lshlrev_b32_e32 v0, 2, v58
	v_lshl_add_u64 v[30:31], s[14:15], 0, v[0:1]
	s_and_b64 s[14:15], exec, s[2:3]
	s_mov_b32 s29, 0
	s_cselect_b32 s28, 0, 0x3f000
	v_lshl_add_u64 v[10:11], v[30:31], 0, s[28:29]
	global_load_dwordx4 v[10:13], v[10:11], off
	s_lshr_b32 s13, s10, 7
	s_lshl_b32 s14, s12, 1
	s_lshl_b32 s38, s13, 4
	s_lshl_b64 s[48:49], s[4:5], 24
	s_cmp_le_u32 s14, s13
	s_cselect_b64 s[30:31], -1, 0
	s_lshl_b32 s39, s12, 5
	s_lshl_b32 s28, s12, 6
	s_or_b32 s40, s14, 1
	v_xor_b32_e32 v0, s8, v63
	s_cmp_lt_u32 s14, s13
	v_lshl_add_u32 v70, v0, 4, v90
	v_xor_b32_e32 v0, v16, v63
	v_lshl_or_b32 v16, s12, 4, v50
	s_cselect_b64 s[34:35], -1, 0
	s_lshl_b32 s12, s40, 4
	s_lshl_b32 s47, s40, 5
	s_and_b64 s[50:51], exec, s[2:3]
	s_cselect_b32 s41, s76, s36
	s_cselect_b32 s40, s77, s33
	s_add_u32 s41, s41, s48
	v_mov_b32_e32 v15, v1
	s_waitcnt vmcnt(22)
	v_or_b32_e32 v18, s39, v50
	s_addc_u32 s40, s40, s49
	v_lshl_add_u32 v71, v0, 4, v92
	v_lshl_add_u64 v[32:33], s[6:7], 0, v[14:15]
	v_or_b32_e32 v0, s38, v50
	s_movk_i32 s6, 0x110
	v_mul_u32_u24_e32 v17, 0x110, v16
	v_mad_u32_u24 v114, v16, s37, 0
	v_lshl_or_b32 v16, s8, 4, v50
	v_mul_u32_u24_e32 v19, 0x110, v18
	v_or_b32_e32 v18, s39, v58
	s_add_u32 s20, s41, s20
	v_mul_lo_u32 v15, v0, s6
	v_mul_lo_u32 v16, v16, s37
	v_cmp_gt_u32_e64 s[4:5], v18, v0
	v_cmp_lt_u32_e64 s[6:7], v18, v0
	v_or_b32_e32 v20, 2, v18
	v_or_b32_e32 v18, 3, v18
	s_addc_u32 s40, s40, 0
	v_add_u32_e32 v115, 0, v16
	v_lshl_add_u32 v16, s8, 5, v94
	s_mulk_i32 s8, 0x880
	s_mulk_i32 s9, 0x110
	v_cmp_gt_u32_e64 s[10:11], v18, v0
	v_or_b32_e32 v18, s12, v50
	s_add_u32 s20, s20, s21
	v_add_u32_e32 v116, s8, v89
	v_add_u32_e32 v117, s9, v89
	v_cmp_gt_u32_e64 s[8:9], v20, v0
	v_mul_u32_u24_e32 v20, 0x110, v18
	v_or_b32_e32 v18, s12, v58
	s_addc_u32 s21, s40, 0
	v_cmp_gt_u32_e64 s[12:13], v18, v0
	v_cmp_lt_u32_e64 s[14:15], v18, v0
	v_or_b32_e32 v21, 2, v18
	v_or_b32_e32 v18, 3, v18
	s_add_u32 s20, s20, s39
	v_mul_lo_u32 v14, v0, s37
	v_cmp_gt_u32_e64 s[16:17], v21, v0
	v_cmp_gt_u32_e64 s[18:19], v18, v0
	s_addc_u32 s21, s21, 0
	v_lshlrev_b32_e32 v0, 1, v50
	v_mov_b32_e32 v18, 0
	s_mov_b32 s46, 1
	v_add_u32_e32 v113, v91, v14
	v_lshl_add_u64 v[34:35], s[20:21], 0, v[0:1]
	v_subrev_u32_e32 v0, s39, v106
	s_sub_i32 s48, 0, s25
	v_or_b32_e32 v118, s38, v58
	v_subrev_u32_e32 v119, s38, v104
	v_or_b32_e32 v120, s39, v74
	s_mov_b32 s49, 62
	v_add_u32_e32 v121, v99, v19
	v_add_u32_e32 v122, v99, v20
	v_add_u32_e32 v123, v100, v17
	v_add_u32_e32 v124, v93, v14
	v_add_u32_e32 v125, v16, v96
	v_add_u32_e32 v126, v99, v15
	s_mov_b32 s50, s29
	v_mov_b32_e32 v19, v18
	v_mov_b32_e32 v20, v18
	v_mov_b32_e32 v21, v18
	v_mov_b32_e32 v14, v18
	v_mov_b32_e32 v15, v18
	v_mov_b32_e32 v16, v18
	v_mov_b32_e32 v17, v18
	s_and_b64 s[94:95], s[2:3], exec
	s_cselect_b32 s93, 0, -1
	v_readfirstlane_b32 s54, v26
	v_readfirstlane_b32 s55, v27
	v_readfirstlane_b32 s56, v28
	v_readfirstlane_b32 s57, v29
	v_readfirstlane_b32 s58, v32
	v_readfirstlane_b32 s59, v33
	v_readfirstlane_b32 s60, v34
	v_readfirstlane_b32 s61, v35
	s_lshl_b32 s94, s24, 1
	s_add_i32 s95, s25, 64
	s_sub_i32 s96, 0xfb8, s25
	s_cmp_eq_u32 s93, 0
	s_cselect_b32 s95, s95, s96
	s_mul_i32 s96, s95, s94
	s_add_u32 s54, s54, s96
	s_addc_u32 s55, s55, 0
	s_mul_i32 s96, s95, 0x4800
	s_add_u32 s56, s56, s96
	s_addc_u32 s57, s57, 0
	s_cmp_eq_u32 s93, 0
	s_cselect_b32 s95, 64, 0xf80
	s_mul_i32 s96, s95, 0x4800
	s_add_u32 s58, s58, s96
	s_addc_u32 s59, s59, 0
	s_and_b32 s96, s93, 0xfc0000
	s_add_u32 s60, s60, s96
	s_addc_u32 s61, s61, 0
	s_lshl_b32 s62, s94, 6
	s_xor_b32 s62, s62, s93
	s_sub_i32 s62, s62, s93
	s_xor_b32 s63, s93, 0x120000
	s_sub_i32 s63, s63, s93
	s_xor_b32 s92, s93, 0x40000
	s_sub_i32 s92, s92, s93
	v_lshlrev_b32_e32 v140, 2, v220
	s_mul_i32 s95, s94, 7
	s_and_b32 s95, s95, s93
	v_add_u32_e32 v140, s95, v140
	s_xor_b32 s95, s94, s93
	s_sub_i32 s95, s95, s93
	v_add_u32_e32 v141, s95, v140
	v_add_u32_e32 v142, s95, v141
	v_add_u32_e32 v143, s95, v142
	v_add_u32_e32 v144, s95, v143
	v_add_u32_e32 v145, s95, v144
	v_add_u32_e32 v146, s95, v145
	v_add_u32_e32 v147, s95, v146
	v_lshlrev_b32_e32 v148, 2, v220
	s_and_b32 s95, s93, 0x1f800
	v_add_u32_e32 v148, s95, v148
	s_xor_b32 s95, s93, 0x4800
	s_sub_i32 s95, s95, s93
	v_add_u32_e32 v149, s95, v148
	v_add_u32_e32 v150, s95, v149
	v_add_u32_e32 v151, s95, v150
	v_add_u32_e32 v152, s95, v151
	v_add_u32_e32 v153, s95, v152
	v_add_u32_e32 v154, s95, v153
	v_add_u32_e32 v155, s95, v154
	s_and_b32 s96, s93, 64
	v_xor_b32_e32 v156, s93, v120
	v_add_u32_e32 v156, s96, v156
	v_mul_u32_u24_e32 v156, 0x4800, v156
	v_lshl_add_u32 v156, v50, 2, v156
	v_add_u32_e32 v157, s95, v156
	v_add_u32_e32 v158, s95, v157
	v_add_u32_e32 v159, s95, v158
	v_add_u32_e32 v160, s95, v159
	v_add_u32_e32 v161, s95, v160
	v_add_u32_e32 v162, s95, v161
	v_add_u32_e32 v163, s95, v162
	v_xor_b32_e32 v164, s93, v118
	v_add_u32_e32 v164, s96, v164
	v_lshlrev_b32_e32 v164, 12, v164
	v_lshl_add_u32 v164, v50, 1, v164
	s_xor_b32 s95, s93, 0x1000
	s_sub_i32 s95, s95, s93
	v_add_u32_e32 v165, s95, v164
	v_add_u32_e32 v166, s95, v165
	v_add_u32_e32 v167, s95, v166
	v_add_u32_e32 v222, v114, v81
	v_add_u32_e32 v223, v114, v82
	v_add_u32_e32 v224, v115, v81
	v_add_u32_e32 v225, v115, v82
	v_add_u32_e32 v226, v95, v81
	v_add_u32_e32 v227, v95, v82
	v_add_u32_e32 v228, s28, v113
	v_add_u32_e32 v229, s47, v113
	v_and_b32_e32 v0, 31, v220
	v_lshrrev_b32_e32 v230, 5, v220
	v_lshl_or_b32 v231, v0, 1, v230
	v_mul_u32_u24_e32 v230, 0x110, v230
	v_lshl_add_u32 v230, v0, 3, v230
	s_mul_i32 s95, s25, 0x110
	v_add_u32_e32 v230, s95, v230
	s_lshr_b32 s95, s25, 3
	v_and_b32_e32 v0, 7, v231
	v_xor_b32_e32 v0, s95, v0
	v_mul_u32_u24_e32 v231, 0x120, v231
	v_lshl_add_u32 v231, v0, 4, v231
	v_lshrrev_b32_e32 v0, 5, v220
	s_and_b32 s95, s93, 7
	v_xor_b32_e32 v0, s95, v0
	v_and_b32_e32 v141, 31, v220
	v_lshlrev_b32_e32 v141, 3, v141
	v_mad_u32_u24 v140, v0, s94, v141
	v_mul_u32_u24_e32 v148, 0x4800, v0
	v_add_u32_e32 v148, v148, v141
	s_lshl_b32 s95, s94, 1
	s_xor_b32 s95, s95, s93
	s_sub_i32 s95, s95, s93
	v_add_u32_e32 v141, s95, v140
	v_add_u32_e32 v142, s95, v141
	v_add_u32_e32 v143, s95, v142
	s_xor_b32 s95, s93, 0x9000
	s_sub_i32 s95, s95, s93
	v_add_u32_e32 v149, s95, v148
	v_add_u32_e32 v150, s95, v149
	v_add_u32_e32 v151, s95, v150
	s_waitcnt vmcnt(0)
	s_sub_u32 s96, s54, s62
	s_subb_u32 s97, s55, s93
	s_sub_u32 s98, s56, s63
	s_subb_u32 s99, s57, s93
	global_load_dwordx2 v[40:41], v140, s[96:97]
	global_load_dwordx2 v[48:49], v148, s[98:99]
	global_load_dwordx2 v[42:43], v141, s[96:97]
	global_load_dwordx2 v[64:65], v149, s[98:99]
	global_load_dwordx2 v[44:45], v142, s[96:97]
	global_load_dwordx2 v[66:67], v150, s[98:99]
	global_load_dwordx2 v[46:47], v143, s[96:97]
	global_load_dwordx2 v[68:69], v151, s[98:99]
	global_load_dwordx2 v[232:233], v140, s[54:55]
	global_load_dwordx2 v[240:241], v148, s[56:57]
	global_load_dwordx2 v[234:235], v141, s[54:55]
	global_load_dwordx2 v[242:243], v149, s[56:57]
	global_load_dwordx2 v[236:237], v142, s[54:55]
	global_load_dwordx2 v[244:245], v150, s[56:57]
	global_load_dwordx2 v[238:239], v143, s[54:55]
	global_load_dwordx2 v[246:247], v151, s[56:57]
	s_add_u32 s54, s54, s62
	s_addc_u32 s55, s55, s93
	s_add_u32 s56, s56, s63
	s_addc_u32 s57, s57, s93
	s_andn2_b64 vcc, exec, s[26:27]
	s_cbranch_vccnz .Lhg_setup_done
	global_load_dword v248, v156, s[58:59] offset:2048 nt
	global_load_dword v249, v157, s[58:59] offset:2048 nt
	global_load_dword v252, v158, s[58:59] offset:2048 nt
	global_load_dword v253, v159, s[58:59] offset:2048 nt
	global_load_dword v254, v160, s[58:59] offset:2048 nt
	global_load_dword v255, v161, s[58:59] offset:2048 nt
	global_load_dword v127, v162, s[58:59] offset:2048 nt
	global_load_dword v0, v163, s[58:59] offset:2048 nt
	s_add_u32 s58, s58, s63
	s_addc_u32 s59, s59, s93
.Lhg_setup_done:
	s_waitcnt vmcnt(0)
	s_branch .LBB0_501
.LBB0_501:
	s_andn2_b64 vcc, exec, s[26:27]
	s_cbranch_vccnz .Lhg_tw_hi_0
	s_waitcnt vmcnt(25)
	s_branch .Lhg_tw_done_0
.Lhg_tw_hi_0:
	s_waitcnt vmcnt(17)
.Lhg_tw_done_0:
	ds_write_b64 v230, v[40:41]
	ds_write_b64 v230, v[42:43] offset:544
	ds_write_b64 v230, v[44:45] offset:1088
	ds_write_b64 v230, v[46:47] offset:1632
	ds_write_b64 v230, v[48:49] offset:17408
	ds_write_b64 v230, v[64:65] offset:17952
	ds_write_b64 v230, v[66:67] offset:18496
	ds_write_b64 v230, v[68:69] offset:19040
	v_permlane32_swap_b32 v48, v49
	v_permlane32_swap_b32 v64, v65
	v_permlane32_swap_b32 v66, v67
	v_permlane32_swap_b32 v68, v69
	v_lshlrev_b32_e32 v22, 16, v49
	v_lshlrev_b32_e32 v23, 16, v65
	v_lshlrev_b32_e32 v24, 16, v67
	v_lshlrev_b32_e32 v25, 16, v69
	v_and_or_b32 v22, v48, s43, v22
	v_and_or_b32 v23, v64, s43, v23
	v_and_or_b32 v24, v66, s43, v24
	v_and_or_b32 v25, v68, s43, v25
	v_lshrrev_b32_e32 v36, 16, v48
	v_lshrrev_b32_e32 v37, 16, v64
	v_lshrrev_b32_e32 v38, 16, v66
	v_lshrrev_b32_e32 v39, 16, v68
	ds_write_b128 v231, v[22:25] offset:34816
	v_and_or_b32 v36, v49, s44, v36
	v_and_or_b32 v37, v65, s44, v37
	v_and_or_b32 v38, v67, s44, v38
	v_and_or_b32 v39, v69, s44, v39
	s_andn2_b64 vcc, exec, s[26:27]
	ds_write_b128 v231, v[36:39] offset:34960
	s_cbranch_vccnz .Lhg_p1e_0
	v_lshlrev_b32_e32 v22, 16, v3
	v_lshlrev_b32_e32 v23, 16, v5
	v_lshlrev_b32_e32 v24, 16, v7
	v_lshlrev_b32_e32 v25, 16, v9
	v_and_or_b32 v22, v2, s43, v22
	v_and_or_b32 v23, v4, s43, v23
	v_and_or_b32 v24, v6, s43, v24
	v_and_or_b32 v25, v8, s43, v25
	v_lshrrev_b32_e32 v36, 16, v2
	v_lshrrev_b32_e32 v37, 16, v4
	v_lshrrev_b32_e32 v38, 16, v6
	v_lshrrev_b32_e32 v39, 16, v8
	v_and_or_b32 v36, v3, s44, v36
	v_and_or_b32 v37, v5, s44, v37
	v_and_or_b32 v38, v7, s44, v38
	v_and_or_b32 v39, v9, s44, v39
	ds_write_b128 v71, v[22:25] offset:53248
	ds_write_b128 v71, v[36:39] offset:53392
.Lhg_p1e_0:
	s_waitcnt lgkmcnt(0)
	s_barrier
	s_andn2_b64 vcc, exec, s[30:31]
	s_cbranch_vccnz .Lhg_v0_0
	s_andn2_b64 vcc, exec, s[34:35]
	s_cbranch_vccnz .Lhg_v1_0
	ds_read_b128 v[168:171], v126
	ds_read_b128 v[184:187], v121 offset:17408
	ds_read_b128 v[200:203], v122 offset:17408
	ds_read_b128 v[128:131], v123
	ds_read_b128 v[172:175], v126 offset:64
	ds_read_b128 v[188:191], v121 offset:17472
	ds_read_b128 v[204:207], v122 offset:17472
	ds_read_b128 v[132:135], v123 offset:64
	ds_read_b128 v[176:179], v126 offset:128
	ds_read_b128 v[192:195], v121 offset:17536
	ds_read_b128 v[208:211], v122 offset:17536
	ds_read_b128 v[136:139], v123 offset:128
	ds_read_b128 v[180:183], v126 offset:192
	ds_read_b128 v[196:199], v121 offset:17600
	ds_read_b128 v[212:215], v122 offset:17600
	ds_read_b128 v[216:219], v123 offset:192
	s_cmpk_ge_i32 s50, 0xf100
	s_cselect_b32 s96, s62, 0
	s_cselect_b32 s97, s63, 0
	s_cselect_b32 s98, s93, 0
	s_and_b64 s[94:95], exec, s[2:3]
	s_cselect_b32 s94, s46, s49
	s_ashr_i32 s95, s94, 31
	s_lshl_b64 s[94:95], s[94:95], 12
	v_lshl_add_u64 v[22:23], v[30:31], 0, s[94:95]
	global_load_dwordx4 v[22:25], v[22:23], off
	global_load_dwordx2 v[40:41], v140, s[54:55]
	global_load_dwordx2 v[48:49], v148, s[56:57]
	v_pk_mul_f32 v[20:21], v[12:13], v[20:21]
	v_pk_mul_f32 v[18:19], v[10:11], v[18:19]
	v_pk_mul_f32 v[12:13], v[12:13], v[16:17]
	v_pk_mul_f32 v[10:11], v[10:11], v[14:15]
	s_add_i32 s49, s49, -1
	s_add_i32 s46, s46, 1
	s_waitcnt lgkmcnt(14)
	v_mfma_f32_16x16x32_bf16 v[36:39], v[184:187], v[168:171], 0
	s_waitcnt lgkmcnt(13)
	v_mfma_f32_16x16x32_bf16 v[26:29], v[200:203], v[168:171], 0
	s_waitcnt lgkmcnt(12)
	v_mfma_f32_16x16x32_bf16 v[32:35], v[168:171], v[128:131], 0
	global_load_dwordx2 v[42:43], v141, s[54:55]
	s_waitcnt lgkmcnt(10)
	v_mfma_f32_16x16x32_bf16 v[36:39], v[188:191], v[172:175], v[36:39]
	s_waitcnt lgkmcnt(9)
	v_mfma_f32_16x16x32_bf16 v[26:29], v[204:207], v[172:175], v[26:29]
	s_waitcnt lgkmcnt(8)
	v_mfma_f32_16x16x32_bf16 v[32:35], v[172:175], v[132:135], v[32:35]
	global_load_dwordx2 v[64:65], v149, s[56:57]
	s_waitcnt lgkmcnt(6)
	v_mfma_f32_16x16x32_bf16 v[36:39], v[192:195], v[176:179], v[36:39]
	s_waitcnt lgkmcnt(5)
	v_mfma_f32_16x16x32_bf16 v[26:29], v[208:211], v[176:179], v[26:29]
	s_waitcnt lgkmcnt(4)
	v_mfma_f32_16x16x32_bf16 v[32:35], v[176:179], v[136:139], v[32:35]
	global_load_dwordx2 v[44:45], v142, s[54:55]
	s_waitcnt lgkmcnt(2)
	v_mfma_f32_16x16x32_bf16 v[36:39], v[196:199], v[180:183], v[36:39]
	s_waitcnt lgkmcnt(1)
	v_mfma_f32_16x16x32_bf16 v[26:29], v[212:215], v[180:183], v[26:29]
	s_waitcnt lgkmcnt(0)
	v_mfma_f32_16x16x32_bf16 v[32:35], v[180:183], v[216:219], v[32:35]
	global_load_dwordx2 v[66:67], v150, s[56:57]
	s_nop 7
	v_cndmask_b32_e64 v36, v36, 0, s[4:5]
	v_cndmask_b32_e64 v37, 0, v37, s[6:7]
	v_cndmask_b32_e64 v38, v38, 0, s[8:9]
	v_cndmask_b32_e64 v39, v39, 0, s[10:11]
	v_cvt_pk_bf16_f32 v36, v36, v37
	v_cvt_pk_bf16_f32 v37, v38, v39
	ds_write_b64 v228, v[36:37] offset:57856
	v_cndmask_b32_e64 v26, v26, 0, s[12:13]
	v_cndmask_b32_e64 v27, 0, v27, s[14:15]
	v_cndmask_b32_e64 v28, v28, 0, s[16:17]
	v_cndmask_b32_e64 v29, v29, 0, s[18:19]
	v_cvt_pk_bf16_f32 v26, v26, v27
	v_cvt_pk_bf16_f32 v27, v28, v29
	ds_write_b64 v229, v[26:27] offset:57856
	s_branch .Lhg_p3_0
.Lhg_v1_0:
	ds_read_b128 v[168:171], v126
	ds_read_b128 v[184:187], v121 offset:17408
	ds_read_b128 v[128:131], v123
	ds_read_b128 v[172:175], v126 offset:64
	ds_read_b128 v[188:191], v121 offset:17472
	ds_read_b128 v[132:135], v123 offset:64
	ds_read_b128 v[176:179], v126 offset:128
	ds_read_b128 v[192:195], v121 offset:17536
	ds_read_b128 v[136:139], v123 offset:128
	ds_read_b128 v[180:183], v126 offset:192
	ds_read_b128 v[196:199], v121 offset:17600
	ds_read_b128 v[216:219], v123 offset:192
	s_cmpk_ge_i32 s50, 0xf100
	s_cselect_b32 s96, s62, 0
	s_cselect_b32 s97, s63, 0
	s_cselect_b32 s98, s93, 0
	s_and_b64 s[94:95], exec, s[2:3]
	s_cselect_b32 s94, s46, s49
	s_ashr_i32 s95, s94, 31
	s_lshl_b64 s[94:95], s[94:95], 12
	v_lshl_add_u64 v[22:23], v[30:31], 0, s[94:95]
	global_load_dwordx4 v[22:25], v[22:23], off
	global_load_dwordx2 v[40:41], v140, s[54:55]
	global_load_dwordx2 v[48:49], v148, s[56:57]
	v_pk_mul_f32 v[20:21], v[12:13], v[20:21]
	v_pk_mul_f32 v[18:19], v[10:11], v[18:19]
	v_pk_mul_f32 v[12:13], v[12:13], v[16:17]
	v_pk_mul_f32 v[10:11], v[10:11], v[14:15]
	s_add_i32 s49, s49, -1
	s_add_i32 s46, s46, 1
	s_waitcnt lgkmcnt(10)
	v_mfma_f32_16x16x32_bf16 v[36:39], v[184:187], v[168:171], 0
	s_waitcnt lgkmcnt(9)
	v_mfma_f32_16x16x32_bf16 v[32:35], v[168:171], v[128:131], 0
	global_load_dwordx2 v[42:43], v141, s[54:55]
	s_waitcnt lgkmcnt(7)
	v_mfma_f32_16x16x32_bf16 v[36:39], v[188:191], v[172:175], v[36:39]
	s_waitcnt lgkmcnt(6)
	v_mfma_f32_16x16x32_bf16 v[32:35], v[172:175], v[132:135], v[32:35]
	global_load_dwordx2 v[64:65], v149, s[56:57]
	s_waitcnt lgkmcnt(4)
	v_mfma_f32_16x16x32_bf16 v[36:39], v[192:195], v[176:179], v[36:39]
	s_waitcnt lgkmcnt(3)
	v_mfma_f32_16x16x32_bf16 v[32:35], v[176:179], v[136:139], v[32:35]
	global_load_dwordx2 v[44:45], v142, s[54:55]
	s_waitcnt lgkmcnt(1)
	v_mfma_f32_16x16x32_bf16 v[36:39], v[196:199], v[180:183], v[36:39]
	s_waitcnt lgkmcnt(0)
	v_mfma_f32_16x16x32_bf16 v[32:35], v[180:183], v[216:219], v[32:35]
	global_load_dwordx2 v[66:67], v150, s[56:57]
	s_nop 7
	v_cndmask_b32_e64 v36, v36, 0, s[4:5]
	v_cndmask_b32_e64 v37, 0, v37, s[6:7]
	v_cndmask_b32_e64 v38, v38, 0, s[8:9]
	v_cndmask_b32_e64 v39, v39, 0, s[10:11]
	v_cvt_pk_bf16_f32 v36, v36, v37
	v_cvt_pk_bf16_f32 v37, v38, v39
	ds_write_b64 v228, v[36:37] offset:57856
	v_mov_b32_e32 v26, 0
	v_mov_b32_e32 v27, 0
	ds_write_b64 v229, v[26:27] offset:57856
	s_branch .Lhg_p3_0
.Lhg_v0_0:
	ds_read_b128 v[168:171], v126
	ds_read_b128 v[128:131], v123
	ds_read_b128 v[172:175], v126 offset:64
	ds_read_b128 v[132:135], v123 offset:64
	ds_read_b128 v[176:179], v126 offset:128
	ds_read_b128 v[136:139], v123 offset:128
	ds_read_b128 v[180:183], v126 offset:192
	ds_read_b128 v[216:219], v123 offset:192
	s_cmpk_ge_i32 s50, 0xf100
	s_cselect_b32 s96, s62, 0
	s_cselect_b32 s97, s63, 0
	s_cselect_b32 s98, s93, 0
	s_and_b64 s[94:95], exec, s[2:3]
	s_cselect_b32 s94, s46, s49
	s_ashr_i32 s95, s94, 31
	s_lshl_b64 s[94:95], s[94:95], 12
	v_lshl_add_u64 v[22:23], v[30:31], 0, s[94:95]
	global_load_dwordx4 v[22:25], v[22:23], off
	global_load_dwordx2 v[40:41], v140, s[54:55]
	global_load_dwordx2 v[48:49], v148, s[56:57]
	v_pk_mul_f32 v[20:21], v[12:13], v[20:21]
	v_pk_mul_f32 v[18:19], v[10:11], v[18:19]
	v_pk_mul_f32 v[12:13], v[12:13], v[16:17]
	v_pk_mul_f32 v[10:11], v[10:11], v[14:15]
	s_add_i32 s49, s49, -1
	s_add_i32 s46, s46, 1
	s_waitcnt lgkmcnt(6)
	v_mfma_f32_16x16x32_bf16 v[32:35], v[168:171], v[128:131], 0
	global_load_dwordx2 v[42:43], v141, s[54:55]
	s_waitcnt lgkmcnt(4)
	v_mfma_f32_16x16x32_bf16 v[32:35], v[172:175], v[132:135], v[32:35]
	global_load_dwordx2 v[64:65], v149, s[56:57]
	s_waitcnt lgkmcnt(2)
	v_mfma_f32_16x16x32_bf16 v[32:35], v[176:179], v[136:139], v[32:35]
	global_load_dwordx2 v[44:45], v142, s[54:55]
	s_waitcnt lgkmcnt(0)
	v_mfma_f32_16x16x32_bf16 v[32:35], v[180:183], v[216:219], v[32:35]
	global_load_dwordx2 v[66:67], v150, s[56:57]
	v_mov_b32_e32 v26, 0
	v_mov_b32_e32 v27, 0
	ds_write_b64 v228, v[26:27] offset:57856
	ds_write_b64 v229, v[26:27] offset:57856
.Lhg_p3_0:
	s_waitcnt lgkmcnt(0)
	s_barrier
	ds_read_b128 v[168:171], v124 offset:57856
	ds_read_b128 v[172:175], v222 offset:53248
	ds_read_b128 v[176:179], v224 offset:34816
	ds_read_b128 v[180:183], v226 offset:53248
	ds_read_b128 v[184:187], v226 offset:55552
	ds_read_b128 v[188:191], v124 offset:57920
	ds_read_b128 v[192:195], v223 offset:53248
	ds_read_b128 v[196:199], v225 offset:34816
	ds_read_b128 v[200:203], v227 offset:53248
	ds_read_b128 v[204:207], v227 offset:55552
	global_load_dwordx2 v[46:47], v143, s[54:55]
	s_waitcnt lgkmcnt(8)
	v_mfma_f32_16x16x32_bf16 v[32:35], v[168:171], v[172:175], v[32:35]
	global_load_dwordx2 v[68:69], v151, s[56:57]
	s_waitcnt lgkmcnt(6)
	v_mfma_f32_16x16x32_bf16 v[18:21], v[176:179], v[180:183], v[18:21]
	s_andn2_b64 vcc, exec, s[26:27]
	s_cbranch_vccnz .Lhg_rv0_0
	global_load_dword v2, v156, s[58:59] offset:2048 nt
	global_load_dword v3, v157, s[58:59] offset:2048 nt
.Lhg_rv0_0:
	s_waitcnt lgkmcnt(5)
	v_mfma_f32_16x16x32_bf16 v[10:13], v[176:179], v[184:187], v[10:13]
	s_andn2_b64 vcc, exec, s[26:27]
	s_cbranch_vccnz .Lhg_rv1_0
	global_load_dword v4, v158, s[58:59] offset:2048 nt
	global_load_dword v5, v159, s[58:59] offset:2048 nt
.Lhg_rv1_0:
	s_waitcnt lgkmcnt(3)
	v_mfma_f32_16x16x32_bf16 v[32:35], v[188:191], v[192:195], v[32:35]
	s_andn2_b64 vcc, exec, s[26:27]
	s_cbranch_vccnz .Lhg_rv2_0
	global_load_dword v6, v160, s[58:59] offset:2048 nt
	global_load_dword v7, v161, s[58:59] offset:2048 nt
.Lhg_rv2_0:
	s_waitcnt lgkmcnt(1)
	v_mfma_f32_16x16x32_bf16 v[18:21], v[196:199], v[200:203], v[18:21]
	s_andn2_b64 vcc, exec, s[26:27]
	s_cbranch_vccnz .Lhg_rv3_0
	global_load_dword v8, v162, s[58:59] offset:2048 nt
	global_load_dword v9, v163, s[58:59] offset:2048 nt
.Lhg_rv3_0:
	s_waitcnt lgkmcnt(0)
	v_mfma_f32_16x16x32_bf16 v[14:17], v[196:199], v[204:207], v[10:13]
	s_add_u32 s54, s54, s96
	s_addc_u32 s55, s55, s98
	s_add_u32 s56, s56, s97
	s_addc_u32 s57, s57, s98
	s_add_u32 s58, s58, s97
	s_addc_u32 s59, s59, s98
	s_nop 5
	v_cvt_pk_bf16_f32 v128, v32, s0
	v_cvt_pk_bf16_f32 v129, v33, s0
	v_cvt_pk_bf16_f32 v130, v34, s0
	v_cvt_pk_bf16_f32 v131, v35, s0
	global_store_short v164, v128, s[60:61]
	global_store_short v165, v129, s[60:61]
	global_store_short v166, v130, s[60:61]
	global_store_short v167, v131, s[60:61]
	s_add_u32 s60, s60, s92
	s_addc_u32 s61, s61, s93
	s_andn2_b64 vcc, exec, s[26:27]
	s_cbranch_vccnz .Lhg_dw_hi_0
	s_waitcnt vmcnt(20)
	s_branch .Lhg_dw_done_0

.Lhg_dw_done_0:
	v_pk_mul_f32 v[36:37], v[24:25], v[20:21]
	v_pk_mul_f32 v[38:39], v[22:23], v[18:19]
	v_pk_mul_f32 v[26:27], v[24:25], v[16:17]
	v_pk_mul_f32 v[28:29], v[22:23], v[14:15]
	s_nop 0
	v_cvt_pk_bf16_f32 v38, v38, v39
	v_cvt_pk_bf16_f32 v39, v36, v37
	ds_write_b64 v125, v[38:39]
	v_cvt_pk_bf16_f32 v28, v28, v29
	v_cvt_pk_bf16_f32 v29, v26, v27
	ds_write_b64 v125, v[28:29] offset:4352
	s_waitcnt lgkmcnt(0)
	s_barrier
	v_mov_b64_e32 v[10:11], v[22:23]
	v_mov_b64_e32 v[12:13], v[24:25]
	s_sub_i32 s50, s50, 64
	s_andn2_b64 vcc, exec, s[26:27]
	s_cbranch_vccnz .Lhg_tw_hi_1
	s_waitcnt vmcnt(25)
	s_branch .Lhg_tw_done_1

.Lhg_tw_done_1:
	ds_write_b64 v230, v[232:233]
	ds_write_b64 v230, v[234:235] offset:544
	ds_write_b64 v230, v[236:237] offset:1088
	ds_write_b64 v230, v[238:239] offset:1632
	ds_write_b64 v230, v[240:241] offset:17408
	ds_write_b64 v230, v[242:243] offset:17952
	ds_write_b64 v230, v[244:245] offset:18496
	ds_write_b64 v230, v[246:247] offset:19040
	v_permlane32_swap_b32 v240, v241
	v_permlane32_swap_b32 v242, v243
	v_permlane32_swap_b32 v244, v245
	v_permlane32_swap_b32 v246, v247
	v_lshlrev_b32_e32 v22, 16, v241
	v_lshlrev_b32_e32 v23, 16, v243
	v_lshlrev_b32_e32 v24, 16, v245
	v_lshlrev_b32_e32 v25, 16, v247
	v_and_or_b32 v22, v240, s43, v22
	v_and_or_b32 v23, v242, s43, v23
	v_and_or_b32 v24, v244, s43, v24
	v_and_or_b32 v25, v246, s43, v25
	v_lshrrev_b32_e32 v36, 16, v240
	v_lshrrev_b32_e32 v37, 16, v242
	v_lshrrev_b32_e32 v38, 16, v244
	v_lshrrev_b32_e32 v39, 16, v246
	ds_write_b128 v231, v[22:25] offset:34816
	v_and_or_b32 v36, v241, s44, v36
	v_and_or_b32 v37, v243, s44, v37
	v_and_or_b32 v38, v245, s44, v38
	v_and_or_b32 v39, v247, s44, v39
	s_andn2_b64 vcc, exec, s[26:27]
	ds_write_b128 v231, v[36:39] offset:34960
	s_cbranch_vccnz .Lhg_p1e_1
	v_lshlrev_b32_e32 v22, 16, v249
	v_lshlrev_b32_e32 v23, 16, v253
	v_lshlrev_b32_e32 v24, 16, v255
	v_lshlrev_b32_e32 v25, 16, v0
	v_and_or_b32 v22, v248, s43, v22
	v_and_or_b32 v23, v252, s43, v23
	v_and_or_b32 v24, v254, s43, v24
	v_and_or_b32 v25, v127, s43, v25
	v_lshrrev_b32_e32 v36, 16, v248
	v_lshrrev_b32_e32 v37, 16, v252
	v_lshrrev_b32_e32 v38, 16, v254
	v_lshrrev_b32_e32 v39, 16, v127
	v_and_or_b32 v36, v249, s44, v36
	v_and_or_b32 v37, v253, s44, v37
	v_and_or_b32 v38, v255, s44, v38
	v_and_or_b32 v39, v0, s44, v39
	ds_write_b128 v71, v[22:25] offset:53248
	ds_write_b128 v71, v[36:39] offset:53392
.Lhg_p1e_1:
	s_waitcnt lgkmcnt(0)
	s_barrier
	s_andn2_b64 vcc, exec, s[30:31]
	s_cbranch_vccnz .Lhg_v0_1
	s_andn2_b64 vcc, exec, s[34:35]
	s_cbranch_vccnz .Lhg_v1_1
	ds_read_b128 v[168:171], v126
	ds_read_b128 v[184:187], v121 offset:17408
	ds_read_b128 v[200:203], v122 offset:17408
	ds_read_b128 v[128:131], v123
	ds_read_b128 v[172:175], v126 offset:64
	ds_read_b128 v[188:191], v121 offset:17472
	ds_read_b128 v[204:207], v122 offset:17472
	ds_read_b128 v[132:135], v123 offset:64
	ds_read_b128 v[176:179], v126 offset:128
	ds_read_b128 v[192:195], v121 offset:17536
	ds_read_b128 v[208:211], v122 offset:17536
	ds_read_b128 v[136:139], v123 offset:128
	ds_read_b128 v[180:183], v126 offset:192
	ds_read_b128 v[196:199], v121 offset:17600
	ds_read_b128 v[212:215], v122 offset:17600
	ds_read_b128 v[216:219], v123 offset:192
	s_cmpk_ge_i32 s50, 0xf100
	s_cselect_b32 s96, s62, 0
	s_cselect_b32 s97, s63, 0
	s_cselect_b32 s98, s93, 0
	s_and_b64 s[94:95], exec, s[2:3]
	s_cselect_b32 s94, s46, s49
	s_ashr_i32 s95, s94, 31
	s_lshl_b64 s[94:95], s[94:95], 12
	v_lshl_add_u64 v[22:23], v[30:31], 0, s[94:95]
	global_load_dwordx4 v[22:25], v[22:23], off
	global_load_dwordx2 v[232:233], v140, s[54:55]
	global_load_dwordx2 v[240:241], v148, s[56:57]
	v_pk_mul_f32 v[20:21], v[12:13], v[20:21]
	v_pk_mul_f32 v[18:19], v[10:11], v[18:19]
	v_pk_mul_f32 v[12:13], v[12:13], v[16:17]
	v_pk_mul_f32 v[10:11], v[10:11], v[14:15]
	s_add_i32 s49, s49, -1
	s_add_i32 s46, s46, 1
	s_waitcnt lgkmcnt(14)
	v_mfma_f32_16x16x32_bf16 v[36:39], v[184:187], v[168:171], 0
	s_waitcnt lgkmcnt(13)
	v_mfma_f32_16x16x32_bf16 v[26:29], v[200:203], v[168:171], 0
	s_waitcnt lgkmcnt(12)
	v_mfma_f32_16x16x32_bf16 v[32:35], v[168:171], v[128:131], 0
	global_load_dwordx2 v[234:235], v141, s[54:55]
	s_waitcnt lgkmcnt(10)
	v_mfma_f32_16x16x32_bf16 v[36:39], v[188:191], v[172:175], v[36:39]
	s_waitcnt lgkmcnt(9)
	v_mfma_f32_16x16x32_bf16 v[26:29], v[204:207], v[172:175], v[26:29]
	s_waitcnt lgkmcnt(8)
	v_mfma_f32_16x16x32_bf16 v[32:35], v[172:175], v[132:135], v[32:35]
	global_load_dwordx2 v[242:243], v149, s[56:57]
	s_waitcnt lgkmcnt(6)
	v_mfma_f32_16x16x32_bf16 v[36:39], v[192:195], v[176:179], v[36:39]
	s_waitcnt lgkmcnt(5)
	v_mfma_f32_16x16x32_bf16 v[26:29], v[208:211], v[176:179], v[26:29]
	s_waitcnt lgkmcnt(4)
	v_mfma_f32_16x16x32_bf16 v[32:35], v[176:179], v[136:139], v[32:35]
	global_load_dwordx2 v[236:237], v142, s[54:55]
	s_waitcnt lgkmcnt(2)
	v_mfma_f32_16x16x32_bf16 v[36:39], v[196:199], v[180:183], v[36:39]
	s_waitcnt lgkmcnt(1)
	v_mfma_f32_16x16x32_bf16 v[26:29], v[212:215], v[180:183], v[26:29]
	s_waitcnt lgkmcnt(0)
	v_mfma_f32_16x16x32_bf16 v[32:35], v[180:183], v[216:219], v[32:35]
	global_load_dwordx2 v[244:245], v150, s[56:57]
	s_nop 7
	v_cndmask_b32_e64 v36, v36, 0, s[4:5]
	v_cndmask_b32_e64 v37, 0, v37, s[6:7]
	v_cndmask_b32_e64 v38, v38, 0, s[8:9]
	v_cndmask_b32_e64 v39, v39, 0, s[10:11]
	v_cvt_pk_bf16_f32 v36, v36, v37
	v_cvt_pk_bf16_f32 v37, v38, v39
	ds_write_b64 v228, v[36:37] offset:57856
	v_cndmask_b32_e64 v26, v26, 0, s[12:13]
	v_cndmask_b32_e64 v27, 0, v27, s[14:15]
	v_cndmask_b32_e64 v28, v28, 0, s[16:17]
	v_cndmask_b32_e64 v29, v29, 0, s[18:19]
	v_cvt_pk_bf16_f32 v26, v26, v27
	v_cvt_pk_bf16_f32 v27, v28, v29
	ds_write_b64 v229, v[26:27] offset:57856
	s_branch .Lhg_p3_1
.Lhg_v1_1:
	ds_read_b128 v[168:171], v126
	ds_read_b128 v[184:187], v121 offset:17408
	ds_read_b128 v[128:131], v123
	ds_read_b128 v[172:175], v126 offset:64
	ds_read_b128 v[188:191], v121 offset:17472
	ds_read_b128 v[132:135], v123 offset:64
	ds_read_b128 v[176:179], v126 offset:128
	ds_read_b128 v[192:195], v121 offset:17536
	ds_read_b128 v[136:139], v123 offset:128
	ds_read_b128 v[180:183], v126 offset:192
	ds_read_b128 v[196:199], v121 offset:17600
	ds_read_b128 v[216:219], v123 offset:192
	s_cmpk_ge_i32 s50, 0xf100
	s_cselect_b32 s96, s62, 0
	s_cselect_b32 s97, s63, 0
	s_cselect_b32 s98, s93, 0
	s_and_b64 s[94:95], exec, s[2:3]
	s_cselect_b32 s94, s46, s49
	s_ashr_i32 s95, s94, 31
	s_lshl_b64 s[94:95], s[94:95], 12
	v_lshl_add_u64 v[22:23], v[30:31], 0, s[94:95]
	global_load_dwordx4 v[22:25], v[22:23], off
	global_load_dwordx2 v[232:233], v140, s[54:55]
	global_load_dwordx2 v[240:241], v148, s[56:57]
	v_pk_mul_f32 v[20:21], v[12:13], v[20:21]
	v_pk_mul_f32 v[18:19], v[10:11], v[18:19]
	v_pk_mul_f32 v[12:13], v[12:13], v[16:17]
	v_pk_mul_f32 v[10:11], v[10:11], v[14:15]
	s_add_i32 s49, s49, -1
	s_add_i32 s46, s46, 1
	s_waitcnt lgkmcnt(10)
	v_mfma_f32_16x16x32_bf16 v[36:39], v[184:187], v[168:171], 0
	s_waitcnt lgkmcnt(9)
	v_mfma_f32_16x16x32_bf16 v[32:35], v[168:171], v[128:131], 0
	global_load_dwordx2 v[234:235], v141, s[54:55]
	s_waitcnt lgkmcnt(7)
	v_mfma_f32_16x16x32_bf16 v[36:39], v[188:191], v[172:175], v[36:39]
	s_waitcnt lgkmcnt(6)
	v_mfma_f32_16x16x32_bf16 v[32:35], v[172:175], v[132:135], v[32:35]
	global_load_dwordx2 v[242:243], v149, s[56:57]
	s_waitcnt lgkmcnt(4)
	v_mfma_f32_16x16x32_bf16 v[36:39], v[192:195], v[176:179], v[36:39]
	s_waitcnt lgkmcnt(3)
	v_mfma_f32_16x16x32_bf16 v[32:35], v[176:179], v[136:139], v[32:35]
	global_load_dwordx2 v[236:237], v142, s[54:55]
	s_waitcnt lgkmcnt(1)
	v_mfma_f32_16x16x32_bf16 v[36:39], v[196:199], v[180:183], v[36:39]
	s_waitcnt lgkmcnt(0)
	v_mfma_f32_16x16x32_bf16 v[32:35], v[180:183], v[216:219], v[32:35]
	global_load_dwordx2 v[244:245], v150, s[56:57]
	s_nop 7
	v_cndmask_b32_e64 v36, v36, 0, s[4:5]
	v_cndmask_b32_e64 v37, 0, v37, s[6:7]
	v_cndmask_b32_e64 v38, v38, 0, s[8:9]
	v_cndmask_b32_e64 v39, v39, 0, s[10:11]
	v_cvt_pk_bf16_f32 v36, v36, v37
	v_cvt_pk_bf16_f32 v37, v38, v39
	ds_write_b64 v228, v[36:37] offset:57856
	v_mov_b32_e32 v26, 0
	v_mov_b32_e32 v27, 0
	ds_write_b64 v229, v[26:27] offset:57856
	s_branch .Lhg_p3_1
.Lhg_v0_1:
	ds_read_b128 v[168:171], v126
	ds_read_b128 v[128:131], v123
	ds_read_b128 v[172:175], v126 offset:64
	ds_read_b128 v[132:135], v123 offset:64
	ds_read_b128 v[176:179], v126 offset:128
	ds_read_b128 v[136:139], v123 offset:128
	ds_read_b128 v[180:183], v126 offset:192
	ds_read_b128 v[216:219], v123 offset:192
	s_cmpk_ge_i32 s50, 0xf100
	s_cselect_b32 s96, s62, 0
	s_cselect_b32 s97, s63, 0
	s_cselect_b32 s98, s93, 0
	s_and_b64 s[94:95], exec, s[2:3]
	s_cselect_b32 s94, s46, s49
	s_ashr_i32 s95, s94, 31
	s_lshl_b64 s[94:95], s[94:95], 12
	v_lshl_add_u64 v[22:23], v[30:31], 0, s[94:95]
	global_load_dwordx4 v[22:25], v[22:23], off
	global_load_dwordx2 v[232:233], v140, s[54:55]
	global_load_dwordx2 v[240:241], v148, s[56:57]
	v_pk_mul_f32 v[20:21], v[12:13], v[20:21]
	v_pk_mul_f32 v[18:19], v[10:11], v[18:19]
	v_pk_mul_f32 v[12:13], v[12:13], v[16:17]
	v_pk_mul_f32 v[10:11], v[10:11], v[14:15]
	s_add_i32 s49, s49, -1
	s_add_i32 s46, s46, 1
	s_waitcnt lgkmcnt(6)
	v_mfma_f32_16x16x32_bf16 v[32:35], v[168:171], v[128:131], 0
	global_load_dwordx2 v[234:235], v141, s[54:55]
	s_waitcnt lgkmcnt(4)
	v_mfma_f32_16x16x32_bf16 v[32:35], v[172:175], v[132:135], v[32:35]
	global_load_dwordx2 v[242:243], v149, s[56:57]
	s_waitcnt lgkmcnt(2)
	v_mfma_f32_16x16x32_bf16 v[32:35], v[176:179], v[136:139], v[32:35]
	global_load_dwordx2 v[236:237], v142, s[54:55]
	s_waitcnt lgkmcnt(0)
	v_mfma_f32_16x16x32_bf16 v[32:35], v[180:183], v[216:219], v[32:35]
	global_load_dwordx2 v[244:245], v150, s[56:57]
	v_mov_b32_e32 v26, 0
	v_mov_b32_e32 v27, 0
	ds_write_b64 v228, v[26:27] offset:57856
	ds_write_b64 v229, v[26:27] offset:57856
.Lhg_p3_1:
	s_waitcnt lgkmcnt(0)
	s_barrier
	ds_read_b128 v[168:171], v124 offset:57856
	ds_read_b128 v[172:175], v222 offset:53248
	ds_read_b128 v[176:179], v224 offset:34816
	ds_read_b128 v[180:183], v226 offset:53248
	ds_read_b128 v[184:187], v226 offset:55552
	ds_read_b128 v[188:191], v124 offset:57920
	ds_read_b128 v[192:195], v223 offset:53248
	ds_read_b128 v[196:199], v225 offset:34816
	ds_read_b128 v[200:203], v227 offset:53248
	ds_read_b128 v[204:207], v227 offset:55552
	global_load_dwordx2 v[238:239], v143, s[54:55]
	s_waitcnt lgkmcnt(8)
	v_mfma_f32_16x16x32_bf16 v[32:35], v[168:171], v[172:175], v[32:35]
	global_load_dwordx2 v[246:247], v151, s[56:57]
	s_waitcnt lgkmcnt(6)
	v_mfma_f32_16x16x32_bf16 v[18:21], v[176:179], v[180:183], v[18:21]
	s_andn2_b64 vcc, exec, s[26:27]
	s_cbranch_vccnz .Lhg_rv0_1
	global_load_dword v248, v156, s[58:59] offset:2048 nt
	global_load_dword v249, v157, s[58:59] offset:2048 nt
.Lhg_rv0_1:
	s_waitcnt lgkmcnt(5)
	v_mfma_f32_16x16x32_bf16 v[10:13], v[176:179], v[184:187], v[10:13]
	s_andn2_b64 vcc, exec, s[26:27]
	s_cbranch_vccnz .Lhg_rv1_1
	global_load_dword v252, v158, s[58:59] offset:2048 nt
	global_load_dword v253, v159, s[58:59] offset:2048 nt
.Lhg_rv1_1:
	s_waitcnt lgkmcnt(3)
	v_mfma_f32_16x16x32_bf16 v[32:35], v[188:191], v[192:195], v[32:35]
	s_andn2_b64 vcc, exec, s[26:27]
	s_cbranch_vccnz .Lhg_rv2_1
	global_load_dword v254, v160, s[58:59] offset:2048 nt
	global_load_dword v255, v161, s[58:59] offset:2048 nt
.Lhg_rv2_1:
	s_waitcnt lgkmcnt(1)
	v_mfma_f32_16x16x32_bf16 v[18:21], v[196:199], v[200:203], v[18:21]
	s_andn2_b64 vcc, exec, s[26:27]
	s_cbranch_vccnz .Lhg_rv3_1
	global_load_dword v127, v162, s[58:59] offset:2048 nt
	global_load_dword v0, v163, s[58:59] offset:2048 nt

.LBB0_512:
	v_readlane_b32 s0, v251, 36
	v_readlane_b32 s50, v251, 47
	v_readlane_b32 s1, v251, 37
	v_readlane_b32 s51, v251, 48
	s_and_b64 s[0:1], s[50:51], s[0:1]
	v_readlane_b32 s84, v251, 42
	s_andn2_b64 vcc, exec, s[0:1]
	v_readlane_b32 s60, v251, 40
	v_readlane_b32 s62, v251, 38
	v_readlane_b32 s85, v251, 43
	v_readlane_b32 s61, v251, 41
	v_readlane_b32 s63, v251, 39
	s_cbranch_vccnz .LBB0_539
	s_movk_i32 s93, 0x2800
	s_mov_b32 s94, 0
	s_cmpk_lt_i32 s64, 0x80
	s_cbranch_scc1 .Ltail_hgrn
	s_movk_i32 s93, 0x2c00
	s_movk_i32 s94, 0x2400
	s_branch .Ltail_conv

.LBB0_536:
	s_waitcnt vmcnt(0)
	s_cmpk_gt_i32 s60, 0x27ff
	s_barrier
	s_waitcnt vmcnt(0)
	s_barrier
	s_cbranch_scc1 .LBB0_539
